# GEMM K-loops: the two strict DMA certification waits (sub-phases 3 and 4) moved from before BAR1 to behind their MMA block (one more MMA section of LDS-DMA flight time, no added instructions); on top
# speedup vs baseline: 1.0080x; 1.0034x over previous
.LBB0_250:
	s_waitcnt lgkmcnt(0)
	s_barrier
	s_setprio 1
	s_waitcnt lgkmcnt(0)
	v_mfma_f32_16x16x128_f8f6f4 v[126:129], v[26:33], v[58:65], v[126:129]
	v_mfma_f32_16x16x128_f8f6f4 v[122:125], v[18:25], v[58:65], v[122:125]
	v_mfma_f32_16x16x128_f8f6f4 v[110:113], v[26:33], v[50:57], v[110:113]
	v_mfma_f32_16x16x128_f8f6f4 v[106:109], v[18:25], v[50:57], v[106:109]
	v_mfma_f32_16x16x128_f8f6f4 v[94:97], v[26:33], v[42:49], v[94:97]
	v_mfma_f32_16x16x128_f8f6f4 v[90:93], v[18:25], v[42:49], v[90:93]
	v_mfma_f32_16x16x128_f8f6f4 v[78:81], v[26:33], v[34:41], v[78:81]
	v_mfma_f32_16x16x128_f8f6f4 v[74:77], v[18:25], v[34:41], v[74:77]
	s_setprio 0
	s_setprio 1
	v_mfma_f32_16x16x128_f8f6f4 v[118:121], v[10:17], v[58:65], v[118:121]
	v_mfma_f32_16x16x128_f8f6f4 v[114:117], v[2:9], v[58:65], v[114:117]
	v_mfma_f32_16x16x128_f8f6f4 v[102:105], v[10:17], v[50:57], v[102:105]
	v_mfma_f32_16x16x128_f8f6f4 v[98:101], v[2:9], v[50:57], v[98:101]
	v_mfma_f32_16x16x128_f8f6f4 v[86:89], v[10:17], v[42:49], v[86:89]
	v_mfma_f32_16x16x128_f8f6f4 v[82:85], v[2:9], v[42:49], v[82:85]
	v_mfma_f32_16x16x128_f8f6f4 v[70:73], v[10:17], v[34:41], v[70:73]
	v_mfma_f32_16x16x128_f8f6f4 v[66:69], v[2:9], v[34:41], v[66:69]
	s_setprio 0
	s_barrier
	v_add_u32_e32 v14, s53, v205
	v_add_u32_e32 v30, s58, v205
	ds_read_b128 v[2:5], v14
	ds_read_b128 v[6:9], v14 offset:1024
	ds_read_b128 v[10:13], v14 offset:2048
	ds_read_b128 v[14:17], v14 offset:3072
	ds_read_b128 v[18:21], v30
	ds_read_b128 v[22:25], v30 offset:1024
	ds_read_b128 v[26:29], v30 offset:2048
	ds_read_b128 v[30:33], v30 offset:3072
	s_add_u32 s36, s36, 0x530000
	s_addc_u32 s37, s37, 0
	s_mov_b32 m0, s51
	v_lshl_add_u64 v[242:243], s[36:37], 0, v[194:195]
	ds_read_b128 v[34:37], v234 offset:32768
	ds_read_b128 v[38:41], v234 offset:33792
	ds_read_b128 v[42:45], v234 offset:34816
	ds_read_b128 v[46:49], v234 offset:35840
	ds_read_b128 v[50:53], v234 offset:36864
	ds_read_b128 v[54:57], v234 offset:37888
	ds_read_b128 v[58:61], v234 offset:38912
	ds_read_b128 v[62:65], v234 offset:39936
	global_load_lds_dwordx4 v[242:243], off
	v_lshl_add_u64 v[242:243], s[36:37], 0, v[198:199]
	s_mov_b32 m0, s52
	s_nop 0
	global_load_lds_dwordx4 v[242:243], off
	s_waitcnt lgkmcnt(0)
	s_barrier
	s_setprio 1
	s_waitcnt lgkmcnt(0)
	v_mfma_f32_16x16x128_f8f6f4 v[190:193], v[2:9], v[34:41], v[190:193]
	v_mfma_f32_16x16x128_f8f6f4 v[186:189], v[10:17], v[34:41], v[186:189]
	v_mfma_f32_16x16x128_f8f6f4 v[174:177], v[2:9], v[42:49], v[174:177]
	v_mfma_f32_16x16x128_f8f6f4 v[170:173], v[10:17], v[42:49], v[170:173]
	v_mfma_f32_16x16x128_f8f6f4 v[158:161], v[2:9], v[50:57], v[158:161]
	v_mfma_f32_16x16x128_f8f6f4 v[154:157], v[10:17], v[50:57], v[154:157]
	v_mfma_f32_16x16x128_f8f6f4 v[142:145], v[2:9], v[58:65], v[142:145]
	v_mfma_f32_16x16x128_f8f6f4 v[138:141], v[10:17], v[58:65], v[138:141]
	s_setprio 0
	s_setprio 1
	v_mfma_f32_16x16x128_f8f6f4 v[182:185], v[18:25], v[34:41], v[182:185]
	v_mfma_f32_16x16x128_f8f6f4 v[178:181], v[26:33], v[34:41], v[178:181]
	v_mfma_f32_16x16x128_f8f6f4 v[166:169], v[18:25], v[42:49], v[166:169]
	v_mfma_f32_16x16x128_f8f6f4 v[162:165], v[26:33], v[42:49], v[162:165]
	v_mfma_f32_16x16x128_f8f6f4 v[150:153], v[18:25], v[50:57], v[150:153]
	v_mfma_f32_16x16x128_f8f6f4 v[146:149], v[26:33], v[50:57], v[146:149]
	v_mfma_f32_16x16x128_f8f6f4 v[134:137], v[18:25], v[58:65], v[134:137]
	v_mfma_f32_16x16x128_f8f6f4 v[130:133], v[26:33], v[58:65], v[130:133]
	s_setprio 0
	s_waitcnt vmcnt(8)
	s_barrier
	s_mov_b32 m0, s54
	v_lshl_add_u64 v[222:223], v[222:223], 0, s[12:13]
	s_add_u32 s34, s34, 0x40080
	ds_read_b128 v[34:37], v234 offset:49152
	ds_read_b128 v[38:41], v234 offset:50176
	ds_read_b128 v[42:45], v234 offset:51200
	ds_read_b128 v[46:49], v234 offset:52224
	ds_read_b128 v[50:53], v234 offset:53248
	ds_read_b128 v[54:57], v234 offset:54272
	ds_read_b128 v[58:61], v234 offset:55296
	ds_read_b128 v[62:65], v234 offset:56320
	global_load_lds_dwordx4 v[222:223], off
	v_lshl_add_u64 v[222:223], v[224:225], 0, s[12:13]
	s_mov_b32 m0, s55
	s_addc_u32 s35, s35, 0
	global_load_lds_dwordx4 v[222:223], off
	v_lshl_add_u64 v[222:223], s[34:35], 0, v[196:197]
	s_mov_b32 m0, s59
	s_nop 0
	global_load_lds_dwordx4 v[222:223], off
	v_lshl_add_u64 v[222:223], s[34:35], 0, v[200:201]
	s_mov_b32 m0, s60
	s_nop 0
	global_load_lds_dwordx4 v[222:223], off
	v_lshl_add_u64 v[222:223], v[226:227], 0, s[12:13]
	s_mov_b32 m0, s56
	s_nop 0
	global_load_lds_dwordx4 v[222:223], off
	v_lshl_add_u64 v[222:223], v[228:229], 0, s[12:13]
	s_mov_b32 m0, s57
	s_nop 0
	global_load_lds_dwordx4 v[222:223], off
	s_waitcnt lgkmcnt(0)
	s_barrier
	s_setprio 1
	s_waitcnt lgkmcnt(0)
	v_mfma_f32_16x16x128_f8f6f4 v[126:129], v[2:9], v[34:41], v[126:129]
	v_mfma_f32_16x16x128_f8f6f4 v[122:125], v[10:17], v[34:41], v[122:125]
	v_mfma_f32_16x16x128_f8f6f4 v[110:113], v[2:9], v[42:49], v[110:113]
	v_mfma_f32_16x16x128_f8f6f4 v[106:109], v[10:17], v[42:49], v[106:109]
	v_mfma_f32_16x16x128_f8f6f4 v[94:97], v[2:9], v[50:57], v[94:97]
	v_mfma_f32_16x16x128_f8f6f4 v[90:93], v[10:17], v[50:57], v[90:93]
	v_mfma_f32_16x16x128_f8f6f4 v[78:81], v[2:9], v[58:65], v[78:81]
	v_mfma_f32_16x16x128_f8f6f4 v[74:77], v[10:17], v[58:65], v[74:77]
	s_setprio 0
	s_setprio 1
	v_mfma_f32_16x16x128_f8f6f4 v[118:121], v[18:25], v[34:41], v[118:121]
	v_mfma_f32_16x16x128_f8f6f4 v[114:117], v[26:33], v[34:41], v[114:117]
	v_mfma_f32_16x16x128_f8f6f4 v[102:105], v[18:25], v[42:49], v[102:105]
	v_mfma_f32_16x16x128_f8f6f4 v[98:101], v[26:33], v[42:49], v[98:101]
	v_mfma_f32_16x16x128_f8f6f4 v[86:89], v[18:25], v[50:57], v[86:89]
	v_mfma_f32_16x16x128_f8f6f4 v[82:85], v[26:33], v[50:57], v[82:85]
	v_mfma_f32_16x16x128_f8f6f4 v[70:73], v[18:25], v[58:65], v[70:73]
	v_mfma_f32_16x16x128_f8f6f4 v[66:69], v[26:33], v[58:65], v[66:69]
	s_setprio 0
	s_waitcnt vmcnt(8)
	s_barrier
	s_add_i32 s80, s80, 2
	s_add_u32 s30, s30, 0x100
	s_addc_u32 s31, s31, 0
	s_cmp_gt_u32 s80, 13
	s_cbranch_scc1 .LBB0_258

.LBB0_885:
	s_waitcnt lgkmcnt(0)
	s_barrier
	s_setprio 1
	s_waitcnt lgkmcnt(0)
	v_mfma_f32_16x16x128_f8f6f4 v[126:129], v[26:33], v[58:65], v[126:129]
	v_mfma_f32_16x16x128_f8f6f4 v[122:125], v[18:25], v[58:65], v[122:125]
	v_mfma_f32_16x16x128_f8f6f4 v[110:113], v[26:33], v[50:57], v[110:113]
	v_mfma_f32_16x16x128_f8f6f4 v[106:109], v[18:25], v[50:57], v[106:109]
	v_mfma_f32_16x16x128_f8f6f4 v[94:97], v[26:33], v[42:49], v[94:97]
	v_mfma_f32_16x16x128_f8f6f4 v[90:93], v[18:25], v[42:49], v[90:93]
	v_mfma_f32_16x16x128_f8f6f4 v[78:81], v[26:33], v[34:41], v[78:81]
	v_mfma_f32_16x16x128_f8f6f4 v[74:77], v[18:25], v[34:41], v[74:77]
	s_setprio 0
	s_setprio 1
	v_mfma_f32_16x16x128_f8f6f4 v[118:121], v[10:17], v[58:65], v[118:121]
	v_mfma_f32_16x16x128_f8f6f4 v[114:117], v[2:9], v[58:65], v[114:117]
	v_mfma_f32_16x16x128_f8f6f4 v[102:105], v[10:17], v[50:57], v[102:105]
	v_mfma_f32_16x16x128_f8f6f4 v[98:101], v[2:9], v[50:57], v[98:101]
	v_mfma_f32_16x16x128_f8f6f4 v[86:89], v[10:17], v[42:49], v[86:89]
	v_mfma_f32_16x16x128_f8f6f4 v[82:85], v[2:9], v[42:49], v[82:85]
	v_mfma_f32_16x16x128_f8f6f4 v[70:73], v[10:17], v[34:41], v[70:73]
	v_mfma_f32_16x16x128_f8f6f4 v[66:69], v[2:9], v[34:41], v[66:69]
	s_setprio 0
	s_barrier
	v_add_u32_e32 v14, s48, v222
	v_add_u32_e32 v30, s53, v222
	ds_read_b128 v[2:5], v14
	ds_read_b128 v[6:9], v14 offset:1024
	ds_read_b128 v[10:13], v14 offset:2048
	ds_read_b128 v[14:17], v14 offset:3072
	ds_read_b128 v[18:21], v30
	ds_read_b128 v[22:25], v30 offset:1024
	ds_read_b128 v[26:29], v30 offset:2048
	ds_read_b128 v[30:33], v30 offset:3072
	s_add_u32 s28, s28, 0x530000
	s_addc_u32 s29, s29, 0
	s_mov_b32 m0, s42
	v_lshl_add_u64 v[228:229], s[28:29], 0, v[194:195]
	ds_read_b128 v[34:37], v226 offset:32768
	ds_read_b128 v[38:41], v226 offset:33792
	ds_read_b128 v[42:45], v226 offset:34816
	ds_read_b128 v[46:49], v226 offset:35840
	ds_read_b128 v[50:53], v226 offset:36864
	ds_read_b128 v[54:57], v226 offset:37888
	ds_read_b128 v[58:61], v226 offset:38912
	ds_read_b128 v[62:65], v226 offset:39936
	global_load_lds_dwordx4 v[228:229], off
	v_lshl_add_u64 v[228:229], s[28:29], 0, v[198:199]
	s_mov_b32 m0, s43
	s_nop 0
	global_load_lds_dwordx4 v[228:229], off
	s_waitcnt lgkmcnt(0)
	s_barrier
	s_setprio 1
	s_waitcnt lgkmcnt(0)
	v_mfma_f32_16x16x128_f8f6f4 v[190:193], v[2:9], v[34:41], v[190:193]
	v_mfma_f32_16x16x128_f8f6f4 v[186:189], v[10:17], v[34:41], v[186:189]
	v_mfma_f32_16x16x128_f8f6f4 v[174:177], v[2:9], v[42:49], v[174:177]
	v_mfma_f32_16x16x128_f8f6f4 v[170:173], v[10:17], v[42:49], v[170:173]
	v_mfma_f32_16x16x128_f8f6f4 v[158:161], v[2:9], v[50:57], v[158:161]
	v_mfma_f32_16x16x128_f8f6f4 v[154:157], v[10:17], v[50:57], v[154:157]
	v_mfma_f32_16x16x128_f8f6f4 v[142:145], v[2:9], v[58:65], v[142:145]
	v_mfma_f32_16x16x128_f8f6f4 v[138:141], v[10:17], v[58:65], v[138:141]
	s_setprio 0
	s_setprio 1
	v_mfma_f32_16x16x128_f8f6f4 v[182:185], v[18:25], v[34:41], v[182:185]
	v_mfma_f32_16x16x128_f8f6f4 v[178:181], v[26:33], v[34:41], v[178:181]
	v_mfma_f32_16x16x128_f8f6f4 v[166:169], v[18:25], v[42:49], v[166:169]
	v_mfma_f32_16x16x128_f8f6f4 v[162:165], v[26:33], v[42:49], v[162:165]
	v_mfma_f32_16x16x128_f8f6f4 v[150:153], v[18:25], v[50:57], v[150:153]
	v_mfma_f32_16x16x128_f8f6f4 v[146:149], v[26:33], v[50:57], v[146:149]
	v_mfma_f32_16x16x128_f8f6f4 v[134:137], v[18:25], v[58:65], v[134:137]
	v_mfma_f32_16x16x128_f8f6f4 v[130:133], v[26:33], v[58:65], v[130:133]
	s_setprio 0
	s_waitcnt vmcnt(8)
	s_barrier
	s_mov_b32 m0, s49
	v_lshl_add_u64 v[214:215], v[214:215], 0, s[14:15]
	s_add_u32 s26, s26, 0x40080
	ds_read_b128 v[34:37], v226 offset:49152
	ds_read_b128 v[38:41], v226 offset:50176
	ds_read_b128 v[42:45], v226 offset:51200
	ds_read_b128 v[46:49], v226 offset:52224
	ds_read_b128 v[50:53], v226 offset:53248
	ds_read_b128 v[54:57], v226 offset:54272
	ds_read_b128 v[58:61], v226 offset:55296
	ds_read_b128 v[62:65], v226 offset:56320
	global_load_lds_dwordx4 v[214:215], off
	v_lshl_add_u64 v[214:215], v[216:217], 0, s[14:15]
	s_mov_b32 m0, s50
	s_addc_u32 s27, s27, 0
	global_load_lds_dwordx4 v[214:215], off
	v_lshl_add_u64 v[214:215], s[26:27], 0, v[196:197]
	s_mov_b32 m0, s54
	s_nop 0
	global_load_lds_dwordx4 v[214:215], off
	v_lshl_add_u64 v[214:215], s[26:27], 0, v[200:201]
	s_mov_b32 m0, s55
	s_nop 0
	global_load_lds_dwordx4 v[214:215], off
	v_lshl_add_u64 v[214:215], v[218:219], 0, s[16:17]
	s_mov_b32 m0, s51
	s_nop 0
	global_load_lds_dwordx4 v[214:215], off
	v_lshl_add_u64 v[214:215], v[220:221], 0, s[16:17]
	s_mov_b32 m0, s52
	s_nop 0
	global_load_lds_dwordx4 v[214:215], off
	s_waitcnt lgkmcnt(0)
	s_barrier
	s_setprio 1
	s_waitcnt lgkmcnt(0)
	v_mfma_f32_16x16x128_f8f6f4 v[126:129], v[2:9], v[34:41], v[126:129]
	v_mfma_f32_16x16x128_f8f6f4 v[122:125], v[10:17], v[34:41], v[122:125]
	v_mfma_f32_16x16x128_f8f6f4 v[110:113], v[2:9], v[42:49], v[110:113]
	v_mfma_f32_16x16x128_f8f6f4 v[106:109], v[10:17], v[42:49], v[106:109]
	v_mfma_f32_16x16x128_f8f6f4 v[94:97], v[2:9], v[50:57], v[94:97]
	v_mfma_f32_16x16x128_f8f6f4 v[90:93], v[10:17], v[50:57], v[90:93]
	v_mfma_f32_16x16x128_f8f6f4 v[78:81], v[2:9], v[58:65], v[78:81]
	v_mfma_f32_16x16x128_f8f6f4 v[74:77], v[10:17], v[58:65], v[74:77]
	s_setprio 0
	s_setprio 1
	v_mfma_f32_16x16x128_f8f6f4 v[118:121], v[18:25], v[34:41], v[118:121]
	v_mfma_f32_16x16x128_f8f6f4 v[114:117], v[26:33], v[34:41], v[114:117]
	v_mfma_f32_16x16x128_f8f6f4 v[102:105], v[18:25], v[42:49], v[102:105]
	v_mfma_f32_16x16x128_f8f6f4 v[98:101], v[26:33], v[42:49], v[98:101]
	v_mfma_f32_16x16x128_f8f6f4 v[86:89], v[18:25], v[50:57], v[86:89]
	v_mfma_f32_16x16x128_f8f6f4 v[82:85], v[26:33], v[50:57], v[82:85]
	v_mfma_f32_16x16x128_f8f6f4 v[70:73], v[18:25], v[58:65], v[70:73]
	v_mfma_f32_16x16x128_f8f6f4 v[66:69], v[26:33], v[58:65], v[66:69]
	s_setprio 0
	s_waitcnt vmcnt(8)
	s_barrier
	s_add_i32 s70, s70, 2
	s_add_u32 s6, s6, 0x200
	s_addc_u32 s7, s7, 0
	s_add_u32 s68, s68, 0x100
	s_addc_u32 s69, s69, 0
	s_cmp_gt_u32 s70, 13
	s_cbranch_scc1 .LBB0_893

.LBB0_1062:
	s_waitcnt lgkmcnt(0)
	s_barrier
	s_setprio 1
	s_waitcnt lgkmcnt(0)
	v_mfma_f32_16x16x128_f8f6f4 v[126:129], v[26:33], v[58:65], v[126:129]
	v_mfma_f32_16x16x128_f8f6f4 v[122:125], v[18:25], v[58:65], v[122:125]
	v_mfma_f32_16x16x128_f8f6f4 v[114:117], v[26:33], v[50:57], v[114:117]
	v_mfma_f32_16x16x128_f8f6f4 v[106:109], v[18:25], v[50:57], v[106:109]
	v_mfma_f32_16x16x128_f8f6f4 v[98:101], v[26:33], v[42:49], v[98:101]
	v_mfma_f32_16x16x128_f8f6f4 v[90:93], v[18:25], v[42:49], v[90:93]
	v_mfma_f32_16x16x128_f8f6f4 v[82:85], v[26:33], v[34:41], v[82:85]
	v_mfma_f32_16x16x128_f8f6f4 v[74:77], v[18:25], v[34:41], v[74:77]
	s_setprio 0
	s_setprio 1
	v_mfma_f32_16x16x128_f8f6f4 v[118:121], v[10:17], v[58:65], v[118:121]
	v_mfma_f32_16x16x128_f8f6f4 v[110:113], v[2:9], v[58:65], v[110:113]
	v_mfma_f32_16x16x128_f8f6f4 v[102:105], v[10:17], v[50:57], v[102:105]
	v_mfma_f32_16x16x128_f8f6f4 v[94:97], v[2:9], v[50:57], v[94:97]
	v_mfma_f32_16x16x128_f8f6f4 v[86:89], v[10:17], v[42:49], v[86:89]
	v_mfma_f32_16x16x128_f8f6f4 v[78:81], v[2:9], v[42:49], v[78:81]
	v_mfma_f32_16x16x128_f8f6f4 v[70:73], v[10:17], v[34:41], v[70:73]
	v_mfma_f32_16x16x128_f8f6f4 v[66:69], v[2:9], v[34:41], v[66:69]
	s_setprio 0
	s_barrier
	v_add_u32_e32 v14, s58, v222
	v_add_u32_e32 v30, s63, v222
	ds_read_b128 v[2:5], v14
	ds_read_b128 v[6:9], v14 offset:1024
	ds_read_b128 v[10:13], v14 offset:2048
	ds_read_b128 v[14:17], v14 offset:3072
	ds_read_b128 v[18:21], v30
	ds_read_b128 v[22:25], v30 offset:1024
	ds_read_b128 v[26:29], v30 offset:2048
	ds_read_b128 v[30:33], v30 offset:3072
	s_add_u32 s40, s40, 0x40000
	s_addc_u32 s41, s41, 0
	s_mov_b32 m0, s56
	v_lshl_add_u64 v[228:229], s[40:41], 0, v[200:201]
	ds_read_b128 v[34:37], v226 offset:32768
	ds_read_b128 v[38:41], v226 offset:33792
	ds_read_b128 v[42:45], v226 offset:34816
	ds_read_b128 v[46:49], v226 offset:35840
	ds_read_b128 v[50:53], v226 offset:36864
	ds_read_b128 v[54:57], v226 offset:37888
	ds_read_b128 v[58:61], v226 offset:38912
	ds_read_b128 v[62:65], v226 offset:39936
	global_load_lds_dwordx4 v[228:229], off
	v_lshl_add_u64 v[228:229], s[40:41], 0, v[196:197]
	s_mov_b32 m0, s57
	s_nop 0
	global_load_lds_dwordx4 v[228:229], off
	s_waitcnt lgkmcnt(0)
	s_barrier
	s_setprio 1
	s_waitcnt lgkmcnt(0)
	v_mfma_f32_16x16x128_f8f6f4 v[190:193], v[2:9], v[34:41], v[190:193]
	v_mfma_f32_16x16x128_f8f6f4 v[186:189], v[10:17], v[34:41], v[186:189]
	v_mfma_f32_16x16x128_f8f6f4 v[178:181], v[2:9], v[42:49], v[178:181]
	v_mfma_f32_16x16x128_f8f6f4 v[170:173], v[10:17], v[42:49], v[170:173]
	v_mfma_f32_16x16x128_f8f6f4 v[162:165], v[2:9], v[50:57], v[162:165]
	v_mfma_f32_16x16x128_f8f6f4 v[154:157], v[10:17], v[50:57], v[154:157]
	v_mfma_f32_16x16x128_f8f6f4 v[146:149], v[2:9], v[58:65], v[146:149]
	v_mfma_f32_16x16x128_f8f6f4 v[138:141], v[10:17], v[58:65], v[138:141]
	s_setprio 0
	s_setprio 1
	v_mfma_f32_16x16x128_f8f6f4 v[182:185], v[18:25], v[34:41], v[182:185]
	v_mfma_f32_16x16x128_f8f6f4 v[174:177], v[26:33], v[34:41], v[174:177]
	v_mfma_f32_16x16x128_f8f6f4 v[166:169], v[18:25], v[42:49], v[166:169]
	v_mfma_f32_16x16x128_f8f6f4 v[158:161], v[26:33], v[42:49], v[158:161]
	v_mfma_f32_16x16x128_f8f6f4 v[150:153], v[18:25], v[50:57], v[150:153]
	v_mfma_f32_16x16x128_f8f6f4 v[142:145], v[26:33], v[50:57], v[142:145]
	v_mfma_f32_16x16x128_f8f6f4 v[134:137], v[18:25], v[58:65], v[134:137]
	v_mfma_f32_16x16x128_f8f6f4 v[130:133], v[26:33], v[58:65], v[130:133]
	s_setprio 0
	s_waitcnt vmcnt(8)
	s_barrier
	s_mov_b32 m0, s59
	v_lshl_add_u64 v[214:215], v[214:215], 0, s[6:7]
	s_add_u32 s38, s38, 0x40080
	ds_read_b128 v[34:37], v226 offset:49152
	ds_read_b128 v[38:41], v226 offset:50176
	ds_read_b128 v[42:45], v226 offset:51200
	ds_read_b128 v[46:49], v226 offset:52224
	ds_read_b128 v[50:53], v226 offset:53248
	ds_read_b128 v[54:57], v226 offset:54272
	ds_read_b128 v[58:61], v226 offset:55296
	ds_read_b128 v[62:65], v226 offset:56320
	global_load_lds_dwordx4 v[214:215], off
	v_lshl_add_u64 v[214:215], v[216:217], 0, s[6:7]
	s_mov_b32 m0, s60
	s_addc_u32 s39, s39, 0
	global_load_lds_dwordx4 v[214:215], off
	v_lshl_add_u64 v[214:215], s[38:39], 0, v[198:199]
	s_mov_b32 m0, s64
	s_nop 0
	global_load_lds_dwordx4 v[214:215], off
	v_lshl_add_u64 v[214:215], s[38:39], 0, v[194:195]
	s_mov_b32 m0, s65
	s_nop 0
	global_load_lds_dwordx4 v[214:215], off
	v_lshl_add_u64 v[214:215], v[218:219], 0, s[6:7]
	s_mov_b32 m0, s61
	s_nop 0
	global_load_lds_dwordx4 v[214:215], off
	v_lshl_add_u64 v[214:215], v[220:221], 0, s[6:7]
	s_mov_b32 m0, s62
	s_nop 0
	global_load_lds_dwordx4 v[214:215], off
	s_waitcnt lgkmcnt(0)
	s_barrier
	s_setprio 1
	s_waitcnt lgkmcnt(0)
	v_mfma_f32_16x16x128_f8f6f4 v[126:129], v[2:9], v[34:41], v[126:129]
	v_mfma_f32_16x16x128_f8f6f4 v[122:125], v[10:17], v[34:41], v[122:125]
	v_mfma_f32_16x16x128_f8f6f4 v[114:117], v[2:9], v[42:49], v[114:117]
	v_mfma_f32_16x16x128_f8f6f4 v[106:109], v[10:17], v[42:49], v[106:109]
	v_mfma_f32_16x16x128_f8f6f4 v[98:101], v[2:9], v[50:57], v[98:101]
	v_mfma_f32_16x16x128_f8f6f4 v[90:93], v[10:17], v[50:57], v[90:93]
	v_mfma_f32_16x16x128_f8f6f4 v[82:85], v[2:9], v[58:65], v[82:85]
	v_mfma_f32_16x16x128_f8f6f4 v[74:77], v[10:17], v[58:65], v[74:77]
	s_setprio 0
	s_setprio 1
	v_mfma_f32_16x16x128_f8f6f4 v[118:121], v[18:25], v[34:41], v[118:121]
	v_mfma_f32_16x16x128_f8f6f4 v[110:113], v[26:33], v[34:41], v[110:113]
	v_mfma_f32_16x16x128_f8f6f4 v[102:105], v[18:25], v[42:49], v[102:105]
	v_mfma_f32_16x16x128_f8f6f4 v[94:97], v[26:33], v[42:49], v[94:97]
	v_mfma_f32_16x16x128_f8f6f4 v[86:89], v[18:25], v[50:57], v[86:89]
	v_mfma_f32_16x16x128_f8f6f4 v[78:81], v[26:33], v[50:57], v[78:81]
	v_mfma_f32_16x16x128_f8f6f4 v[70:73], v[18:25], v[58:65], v[70:73]
	v_mfma_f32_16x16x128_f8f6f4 v[66:69], v[26:33], v[58:65], v[66:69]
	s_setprio 0
	s_waitcnt vmcnt(8)
	s_barrier
	s_add_i32 s77, s77, 2
	s_add_u32 s36, s36, 0x100
	s_addc_u32 s37, s37, 0
	s_cmp_gt_u32 s77, 13
	s_cbranch_scc1 .LBB0_1070

.LBB0_1225:
	s_waitcnt lgkmcnt(0)
	s_barrier
	s_setprio 1
	s_waitcnt lgkmcnt(0)
	v_mfma_f32_16x16x32_bf16 v[54:57], v[82:85], v[186:189], v[54:57]
	v_mfma_f32_16x16x32_bf16 v[46:49], v[90:93], v[186:189], v[46:49]
	v_mfma_f32_16x16x32_bf16 v[50:53], v[82:85], v[178:181], v[50:53]
	v_mfma_f32_16x16x32_bf16 v[38:41], v[90:93], v[178:181], v[38:41]
	v_mfma_f32_16x16x32_bf16 v[30:33], v[82:85], v[170:173], v[30:33]
	v_mfma_f32_16x16x32_bf16 v[22:25], v[90:93], v[170:173], v[22:25]
	v_mfma_f32_16x16x32_bf16 v[14:17], v[82:85], v[162:165], v[14:17]
	v_mfma_f32_16x16x32_bf16 v[10:13], v[90:93], v[162:165], v[10:13]
	v_mfma_f32_16x16x32_bf16 v[54:57], v[86:89], v[190:193], v[54:57]
	v_mfma_f32_16x16x32_bf16 v[46:49], v[94:97], v[190:193], v[46:49]
	v_mfma_f32_16x16x32_bf16 v[50:53], v[86:89], v[182:185], v[50:53]
	v_mfma_f32_16x16x32_bf16 v[38:41], v[94:97], v[182:185], v[38:41]
	v_mfma_f32_16x16x32_bf16 v[30:33], v[86:89], v[174:177], v[30:33]
	v_mfma_f32_16x16x32_bf16 v[22:25], v[94:97], v[174:177], v[22:25]
	v_mfma_f32_16x16x32_bf16 v[14:17], v[86:89], v[166:169], v[14:17]
	v_mfma_f32_16x16x32_bf16 v[10:13], v[94:97], v[166:169], v[10:13]
	s_setprio 0
	s_setprio 1
	v_mfma_f32_16x16x32_bf16 v[62:65], v[66:69], v[186:189], v[62:65]
	v_mfma_f32_16x16x32_bf16 v[58:61], v[74:77], v[186:189], v[58:61]
	v_mfma_f32_16x16x32_bf16 v[42:45], v[66:69], v[178:181], v[42:45]
	v_mfma_f32_16x16x32_bf16 v[34:37], v[74:77], v[178:181], v[34:37]
	v_mfma_f32_16x16x32_bf16 v[26:29], v[66:69], v[170:173], v[26:29]
	v_mfma_f32_16x16x32_bf16 v[18:21], v[74:77], v[170:173], v[18:21]
	v_mfma_f32_16x16x32_bf16 v[6:9], v[66:69], v[162:165], v[6:9]
	v_mfma_f32_16x16x32_bf16 v[2:5], v[74:77], v[162:165], v[2:5]
	v_mfma_f32_16x16x32_bf16 v[62:65], v[70:73], v[190:193], v[62:65]
	v_mfma_f32_16x16x32_bf16 v[58:61], v[78:81], v[190:193], v[58:61]
	v_mfma_f32_16x16x32_bf16 v[42:45], v[70:73], v[182:185], v[42:45]
	v_mfma_f32_16x16x32_bf16 v[34:37], v[78:81], v[182:185], v[34:37]
	v_mfma_f32_16x16x32_bf16 v[26:29], v[70:73], v[174:177], v[26:29]
	v_mfma_f32_16x16x32_bf16 v[18:21], v[78:81], v[174:177], v[18:21]
	v_mfma_f32_16x16x32_bf16 v[6:9], v[70:73], v[166:169], v[6:9]
	v_mfma_f32_16x16x32_bf16 v[2:5], v[78:81], v[166:169], v[2:5]
	s_setprio 0
	s_barrier
	v_add_u32_e32 v78, s74, v1
	v_add_u32_e32 v94, s79, v1
	ds_read_b128 v[66:69], v78
	ds_read_b128 v[70:73], v78 offset:1024
	ds_read_b128 v[74:77], v78 offset:2048
	ds_read_b128 v[78:81], v78 offset:3072
	ds_read_b128 v[82:85], v94
	ds_read_b128 v[86:89], v94 offset:1024
	ds_read_b128 v[90:93], v94 offset:2048
	ds_read_b128 v[94:97], v94 offset:3072
	s_add_u32 s54, s54, 0x80000
	s_addc_u32 s55, s55, 0
	s_mov_b32 m0, s70
	v_lshl_add_u64 v[234:235], s[54:55], 0, v[194:195]
	ds_read_b128 v[162:165], v231 offset:32768
	ds_read_b128 v[166:169], v231 offset:33792
	ds_read_b128 v[170:173], v231 offset:34816
	ds_read_b128 v[174:177], v231 offset:35840
	ds_read_b128 v[178:181], v231 offset:36864
	ds_read_b128 v[182:185], v231 offset:37888
	ds_read_b128 v[186:189], v231 offset:38912
	ds_read_b128 v[190:193], v231 offset:39936
	global_load_lds_dwordx4 v[234:235], off
	v_lshl_add_u64 v[234:235], s[54:55], 0, v[198:199]
	s_mov_b32 m0, s71
	s_nop 0
	global_load_lds_dwordx4 v[234:235], off
	s_waitcnt lgkmcnt(0)
	s_barrier
	s_setprio 1
	s_waitcnt lgkmcnt(0)
	v_mfma_f32_16x16x32_bf16 v[150:153], v[66:69], v[162:165], v[150:153]
	v_mfma_f32_16x16x32_bf16 v[142:145], v[74:77], v[162:165], v[142:145]
	v_mfma_f32_16x16x32_bf16 v[146:149], v[66:69], v[170:173], v[146:149]
	v_mfma_f32_16x16x32_bf16 v[134:137], v[74:77], v[170:173], v[134:137]
	v_mfma_f32_16x16x32_bf16 v[126:129], v[66:69], v[178:181], v[126:129]
	v_mfma_f32_16x16x32_bf16 v[118:121], v[74:77], v[178:181], v[118:121]
	v_mfma_f32_16x16x32_bf16 v[110:113], v[66:69], v[186:189], v[110:113]
	v_mfma_f32_16x16x32_bf16 v[106:109], v[74:77], v[186:189], v[106:109]
	v_mfma_f32_16x16x32_bf16 v[150:153], v[70:73], v[166:169], v[150:153]
	v_mfma_f32_16x16x32_bf16 v[142:145], v[78:81], v[166:169], v[142:145]
	v_mfma_f32_16x16x32_bf16 v[146:149], v[70:73], v[174:177], v[146:149]
	v_mfma_f32_16x16x32_bf16 v[134:137], v[78:81], v[174:177], v[134:137]
	v_mfma_f32_16x16x32_bf16 v[126:129], v[70:73], v[182:185], v[126:129]
	v_mfma_f32_16x16x32_bf16 v[118:121], v[78:81], v[182:185], v[118:121]
	v_mfma_f32_16x16x32_bf16 v[110:113], v[70:73], v[190:193], v[110:113]
	v_mfma_f32_16x16x32_bf16 v[106:109], v[78:81], v[190:193], v[106:109]
	s_setprio 0
	s_setprio 1
	v_mfma_f32_16x16x32_bf16 v[158:161], v[82:85], v[162:165], v[158:161]
	v_mfma_f32_16x16x32_bf16 v[154:157], v[90:93], v[162:165], v[154:157]
	v_mfma_f32_16x16x32_bf16 v[138:141], v[82:85], v[170:173], v[138:141]
	v_mfma_f32_16x16x32_bf16 v[130:133], v[90:93], v[170:173], v[130:133]
	v_mfma_f32_16x16x32_bf16 v[122:125], v[82:85], v[178:181], v[122:125]
	v_mfma_f32_16x16x32_bf16 v[114:117], v[90:93], v[178:181], v[114:117]
	v_mfma_f32_16x16x32_bf16 v[102:105], v[82:85], v[186:189], v[102:105]
	v_mfma_f32_16x16x32_bf16 v[98:101], v[90:93], v[186:189], v[98:101]
	v_mfma_f32_16x16x32_bf16 v[158:161], v[86:89], v[166:169], v[158:161]
	v_mfma_f32_16x16x32_bf16 v[154:157], v[94:97], v[166:169], v[154:157]
	v_mfma_f32_16x16x32_bf16 v[138:141], v[86:89], v[174:177], v[138:141]
	v_mfma_f32_16x16x32_bf16 v[130:133], v[94:97], v[174:177], v[130:133]
	v_mfma_f32_16x16x32_bf16 v[122:125], v[86:89], v[182:185], v[122:125]
	v_mfma_f32_16x16x32_bf16 v[114:117], v[94:97], v[182:185], v[114:117]
	v_mfma_f32_16x16x32_bf16 v[102:105], v[86:89], v[190:193], v[102:105]
	v_mfma_f32_16x16x32_bf16 v[98:101], v[94:97], v[190:193], v[98:101]
	s_setprio 0
	s_waitcnt vmcnt(8)
	s_barrier
	s_mov_b32 m0, s75
	v_lshl_add_u64 v[220:221], v[220:221], 0, s[24:25]
	s_add_u32 s52, s52, 0x80080
	ds_read_b128 v[162:165], v231 offset:49152
	ds_read_b128 v[166:169], v231 offset:50176
	ds_read_b128 v[170:173], v231 offset:51200
	ds_read_b128 v[174:177], v231 offset:52224
	ds_read_b128 v[178:181], v231 offset:53248
	ds_read_b128 v[182:185], v231 offset:54272
	ds_read_b128 v[186:189], v231 offset:55296
	ds_read_b128 v[190:193], v231 offset:56320
	global_load_lds_dwordx4 v[220:221], off
	v_lshl_add_u64 v[220:221], v[222:223], 0, s[24:25]
	s_mov_b32 m0, s76
	s_addc_u32 s53, s53, 0
	global_load_lds_dwordx4 v[220:221], off
	v_lshl_add_u64 v[220:221], s[52:53], 0, v[196:197]
	s_mov_b32 m0, s80
	s_nop 0
	global_load_lds_dwordx4 v[220:221], off
	v_lshl_add_u64 v[220:221], s[52:53], 0, v[200:201]
	s_mov_b32 m0, s81
	s_nop 0
	global_load_lds_dwordx4 v[220:221], off
	v_lshl_add_u64 v[220:221], v[224:225], 0, s[24:25]
	s_mov_b32 m0, s77
	s_nop 0
	global_load_lds_dwordx4 v[220:221], off
	v_lshl_add_u64 v[220:221], v[226:227], 0, s[24:25]
	s_mov_b32 m0, s78
	s_nop 0
	global_load_lds_dwordx4 v[220:221], off
	s_waitcnt lgkmcnt(0)
	s_barrier
	s_setprio 1
	s_waitcnt lgkmcnt(0)
	v_mfma_f32_16x16x32_bf16 v[54:57], v[66:69], v[162:165], v[54:57]
	v_mfma_f32_16x16x32_bf16 v[46:49], v[74:77], v[162:165], v[46:49]
	v_mfma_f32_16x16x32_bf16 v[50:53], v[66:69], v[170:173], v[50:53]
	v_mfma_f32_16x16x32_bf16 v[38:41], v[74:77], v[170:173], v[38:41]
	v_mfma_f32_16x16x32_bf16 v[30:33], v[66:69], v[178:181], v[30:33]
	v_mfma_f32_16x16x32_bf16 v[22:25], v[74:77], v[178:181], v[22:25]
	v_mfma_f32_16x16x32_bf16 v[14:17], v[66:69], v[186:189], v[14:17]
	v_mfma_f32_16x16x32_bf16 v[10:13], v[74:77], v[186:189], v[10:13]
	v_mfma_f32_16x16x32_bf16 v[54:57], v[70:73], v[166:169], v[54:57]
	v_mfma_f32_16x16x32_bf16 v[46:49], v[78:81], v[166:169], v[46:49]
	v_mfma_f32_16x16x32_bf16 v[50:53], v[70:73], v[174:177], v[50:53]
	v_mfma_f32_16x16x32_bf16 v[38:41], v[78:81], v[174:177], v[38:41]
	v_mfma_f32_16x16x32_bf16 v[30:33], v[70:73], v[182:185], v[30:33]
	v_mfma_f32_16x16x32_bf16 v[22:25], v[78:81], v[182:185], v[22:25]
	v_mfma_f32_16x16x32_bf16 v[14:17], v[70:73], v[190:193], v[14:17]
	v_mfma_f32_16x16x32_bf16 v[10:13], v[78:81], v[190:193], v[10:13]
	s_setprio 0
	s_setprio 1
	v_mfma_f32_16x16x32_bf16 v[62:65], v[82:85], v[162:165], v[62:65]
	v_mfma_f32_16x16x32_bf16 v[58:61], v[90:93], v[162:165], v[58:61]
	v_mfma_f32_16x16x32_bf16 v[42:45], v[82:85], v[170:173], v[42:45]
	v_mfma_f32_16x16x32_bf16 v[34:37], v[90:93], v[170:173], v[34:37]
	v_mfma_f32_16x16x32_bf16 v[26:29], v[82:85], v[178:181], v[26:29]
	v_mfma_f32_16x16x32_bf16 v[18:21], v[90:93], v[178:181], v[18:21]
	v_mfma_f32_16x16x32_bf16 v[6:9], v[82:85], v[186:189], v[6:9]
	v_mfma_f32_16x16x32_bf16 v[2:5], v[90:93], v[186:189], v[2:5]
	v_mfma_f32_16x16x32_bf16 v[62:65], v[86:89], v[166:169], v[62:65]
	v_mfma_f32_16x16x32_bf16 v[58:61], v[94:97], v[166:169], v[58:61]
	v_mfma_f32_16x16x32_bf16 v[42:45], v[86:89], v[174:177], v[42:45]
	v_mfma_f32_16x16x32_bf16 v[34:37], v[94:97], v[174:177], v[34:37]
	v_mfma_f32_16x16x32_bf16 v[26:29], v[86:89], v[182:185], v[26:29]
	v_mfma_f32_16x16x32_bf16 v[18:21], v[94:97], v[182:185], v[18:21]
	v_mfma_f32_16x16x32_bf16 v[6:9], v[86:89], v[190:193], v[6:9]
	v_mfma_f32_16x16x32_bf16 v[2:5], v[94:97], v[190:193], v[2:5]
	s_setprio 0
	s_waitcnt vmcnt(8)
	s_barrier
	s_add_i32 s93, s93, 2
	s_add_u32 s50, s50, 0x100
	s_addc_u32 s51, s51, 0
	s_cmp_gt_u32 s93, 29
	s_cbranch_scc1 .LBB0_1233

.LBB0_1397:
	s_waitcnt lgkmcnt(0)
	s_barrier
	s_setprio 1
	s_waitcnt lgkmcnt(0)
	v_mfma_f32_16x16x32_bf16 v[62:65], v[146:149], v[186:189], v[62:65]
	v_mfma_f32_16x16x32_bf16 v[58:61], v[154:157], v[186:189], v[58:61]
	v_mfma_f32_16x16x32_bf16 v[54:57], v[146:149], v[178:181], v[54:57]
	v_mfma_f32_16x16x32_bf16 v[46:49], v[154:157], v[178:181], v[46:49]
	v_mfma_f32_16x16x32_bf16 v[38:41], v[146:149], v[170:173], v[38:41]
	v_mfma_f32_16x16x32_bf16 v[30:33], v[154:157], v[170:173], v[30:33]
	v_mfma_f32_16x16x32_bf16 v[22:25], v[146:149], v[162:165], v[22:25]
	v_mfma_f32_16x16x32_bf16 v[14:17], v[154:157], v[162:165], v[14:17]
	v_mfma_f32_16x16x32_bf16 v[62:65], v[150:153], v[190:193], v[62:65]
	v_mfma_f32_16x16x32_bf16 v[58:61], v[158:161], v[190:193], v[58:61]
	v_mfma_f32_16x16x32_bf16 v[54:57], v[150:153], v[182:185], v[54:57]
	v_mfma_f32_16x16x32_bf16 v[46:49], v[158:161], v[182:185], v[46:49]
	v_mfma_f32_16x16x32_bf16 v[38:41], v[150:153], v[174:177], v[38:41]
	v_mfma_f32_16x16x32_bf16 v[30:33], v[158:161], v[174:177], v[30:33]
	v_mfma_f32_16x16x32_bf16 v[22:25], v[150:153], v[166:169], v[22:25]
	v_mfma_f32_16x16x32_bf16 v[14:17], v[158:161], v[166:169], v[14:17]
	s_setprio 0
	s_setprio 1
	v_mfma_f32_16x16x32_bf16 v[50:53], v[130:133], v[186:189], v[50:53]
	v_mfma_f32_16x16x32_bf16 v[42:45], v[138:141], v[186:189], v[42:45]
	v_mfma_f32_16x16x32_bf16 v[34:37], v[130:133], v[178:181], v[34:37]
	v_mfma_f32_16x16x32_bf16 v[26:29], v[138:141], v[178:181], v[26:29]
	v_mfma_f32_16x16x32_bf16 v[18:21], v[130:133], v[170:173], v[18:21]
	v_mfma_f32_16x16x32_bf16 v[10:13], v[138:141], v[170:173], v[10:13]
	v_mfma_f32_16x16x32_bf16 v[6:9], v[130:133], v[162:165], v[6:9]
	v_mfma_f32_16x16x32_bf16 v[2:5], v[138:141], v[162:165], v[2:5]
	v_mfma_f32_16x16x32_bf16 v[50:53], v[134:137], v[190:193], v[50:53]
	v_mfma_f32_16x16x32_bf16 v[42:45], v[142:145], v[190:193], v[42:45]
	v_mfma_f32_16x16x32_bf16 v[34:37], v[134:137], v[182:185], v[34:37]
	v_mfma_f32_16x16x32_bf16 v[26:29], v[142:145], v[182:185], v[26:29]
	v_mfma_f32_16x16x32_bf16 v[18:21], v[134:137], v[174:177], v[18:21]
	v_mfma_f32_16x16x32_bf16 v[10:13], v[142:145], v[174:177], v[10:13]
	v_mfma_f32_16x16x32_bf16 v[6:9], v[134:137], v[166:169], v[6:9]
	v_mfma_f32_16x16x32_bf16 v[2:5], v[142:145], v[166:169], v[2:5]
	s_setprio 0
	s_barrier
	v_add_u32_e32 v142, s52, v222
	v_add_u32_e32 v158, s57, v222
	ds_read_b128 v[130:133], v142
	ds_read_b128 v[134:137], v142 offset:1024
	ds_read_b128 v[138:141], v142 offset:2048
	ds_read_b128 v[142:145], v142 offset:3072
	ds_read_b128 v[146:149], v158
	ds_read_b128 v[150:153], v158 offset:1024
	ds_read_b128 v[154:157], v158 offset:2048
	ds_read_b128 v[158:161], v158 offset:3072
	s_add_u32 s30, s30, 0x160000
	s_addc_u32 s31, s31, 0
	s_mov_b32 m0, s50
	v_lshl_add_u64 v[228:229], s[30:31], 0, v[200:201]
	ds_read_b128 v[162:165], v226 offset:32768
	ds_read_b128 v[166:169], v226 offset:33792
	ds_read_b128 v[170:173], v226 offset:34816
	ds_read_b128 v[174:177], v226 offset:35840
	ds_read_b128 v[178:181], v226 offset:36864
	ds_read_b128 v[182:185], v226 offset:37888
	ds_read_b128 v[186:189], v226 offset:38912
	ds_read_b128 v[190:193], v226 offset:39936
	global_load_lds_dwordx4 v[228:229], off
	v_lshl_add_u64 v[228:229], s[30:31], 0, v[196:197]
	s_mov_b32 m0, s51
	s_nop 0
	global_load_lds_dwordx4 v[228:229], off
	s_waitcnt lgkmcnt(0)
	s_barrier
	s_setprio 1
	s_waitcnt lgkmcnt(0)
	v_mfma_f32_16x16x32_bf16 v[126:129], v[130:133], v[162:165], v[126:129]
	v_mfma_f32_16x16x32_bf16 v[122:125], v[138:141], v[162:165], v[122:125]
	v_mfma_f32_16x16x32_bf16 v[118:121], v[130:133], v[170:173], v[118:121]
	v_mfma_f32_16x16x32_bf16 v[110:113], v[138:141], v[170:173], v[110:113]
	v_mfma_f32_16x16x32_bf16 v[102:105], v[130:133], v[178:181], v[102:105]
	v_mfma_f32_16x16x32_bf16 v[94:97], v[138:141], v[178:181], v[94:97]
	v_mfma_f32_16x16x32_bf16 v[86:89], v[130:133], v[186:189], v[86:89]
	v_mfma_f32_16x16x32_bf16 v[78:81], v[138:141], v[186:189], v[78:81]
	v_mfma_f32_16x16x32_bf16 v[126:129], v[134:137], v[166:169], v[126:129]
	v_mfma_f32_16x16x32_bf16 v[122:125], v[142:145], v[166:169], v[122:125]
	v_mfma_f32_16x16x32_bf16 v[118:121], v[134:137], v[174:177], v[118:121]
	v_mfma_f32_16x16x32_bf16 v[110:113], v[142:145], v[174:177], v[110:113]
	v_mfma_f32_16x16x32_bf16 v[102:105], v[134:137], v[182:185], v[102:105]
	v_mfma_f32_16x16x32_bf16 v[94:97], v[142:145], v[182:185], v[94:97]
	v_mfma_f32_16x16x32_bf16 v[86:89], v[134:137], v[190:193], v[86:89]
	v_mfma_f32_16x16x32_bf16 v[78:81], v[142:145], v[190:193], v[78:81]
	s_setprio 0
	s_setprio 1
	v_mfma_f32_16x16x32_bf16 v[114:117], v[146:149], v[162:165], v[114:117]
	v_mfma_f32_16x16x32_bf16 v[106:109], v[154:157], v[162:165], v[106:109]
	v_mfma_f32_16x16x32_bf16 v[98:101], v[146:149], v[170:173], v[98:101]
	v_mfma_f32_16x16x32_bf16 v[90:93], v[154:157], v[170:173], v[90:93]
	v_mfma_f32_16x16x32_bf16 v[82:85], v[146:149], v[178:181], v[82:85]
	v_mfma_f32_16x16x32_bf16 v[74:77], v[154:157], v[178:181], v[74:77]
	v_mfma_f32_16x16x32_bf16 v[70:73], v[146:149], v[186:189], v[70:73]
	v_mfma_f32_16x16x32_bf16 v[66:69], v[154:157], v[186:189], v[66:69]
	v_mfma_f32_16x16x32_bf16 v[114:117], v[150:153], v[166:169], v[114:117]
	v_mfma_f32_16x16x32_bf16 v[106:109], v[158:161], v[166:169], v[106:109]
	v_mfma_f32_16x16x32_bf16 v[98:101], v[150:153], v[174:177], v[98:101]
	v_mfma_f32_16x16x32_bf16 v[90:93], v[158:161], v[174:177], v[90:93]
	v_mfma_f32_16x16x32_bf16 v[82:85], v[150:153], v[182:185], v[82:85]
	v_mfma_f32_16x16x32_bf16 v[74:77], v[158:161], v[182:185], v[74:77]
	v_mfma_f32_16x16x32_bf16 v[70:73], v[150:153], v[190:193], v[70:73]
	v_mfma_f32_16x16x32_bf16 v[66:69], v[158:161], v[190:193], v[66:69]
	s_setprio 0
	s_waitcnt vmcnt(8)
	s_barrier
	s_mov_b32 m0, s53
	v_lshl_add_u64 v[214:215], v[214:215], 0, s[8:9]
	s_add_u32 s28, s28, 0x160080
	ds_read_b128 v[162:165], v226 offset:49152
	ds_read_b128 v[166:169], v226 offset:50176
	ds_read_b128 v[170:173], v226 offset:51200
	ds_read_b128 v[174:177], v226 offset:52224
	ds_read_b128 v[178:181], v226 offset:53248
	ds_read_b128 v[182:185], v226 offset:54272
	ds_read_b128 v[186:189], v226 offset:55296
	ds_read_b128 v[190:193], v226 offset:56320
	global_load_lds_dwordx4 v[214:215], off
	v_lshl_add_u64 v[214:215], v[216:217], 0, s[8:9]
	s_mov_b32 m0, s54
	s_addc_u32 s29, s29, 0
	global_load_lds_dwordx4 v[214:215], off
	v_lshl_add_u64 v[214:215], s[28:29], 0, v[198:199]
	s_mov_b32 m0, s58
	s_nop 0
	global_load_lds_dwordx4 v[214:215], off
	v_lshl_add_u64 v[214:215], s[28:29], 0, v[194:195]
	s_mov_b32 m0, s59
	s_nop 0
	global_load_lds_dwordx4 v[214:215], off
	v_lshl_add_u64 v[214:215], v[218:219], 0, s[8:9]
	s_mov_b32 m0, s55
	s_nop 0
	global_load_lds_dwordx4 v[214:215], off
	v_lshl_add_u64 v[214:215], v[220:221], 0, s[8:9]
	s_mov_b32 m0, s56
	s_nop 0
	global_load_lds_dwordx4 v[214:215], off
	s_waitcnt lgkmcnt(0)
	s_barrier
	s_setprio 1
	s_waitcnt lgkmcnt(0)
	v_mfma_f32_16x16x32_bf16 v[62:65], v[130:133], v[162:165], v[62:65]
	v_mfma_f32_16x16x32_bf16 v[58:61], v[138:141], v[162:165], v[58:61]
	v_mfma_f32_16x16x32_bf16 v[54:57], v[130:133], v[170:173], v[54:57]
	v_mfma_f32_16x16x32_bf16 v[46:49], v[138:141], v[170:173], v[46:49]
	v_mfma_f32_16x16x32_bf16 v[38:41], v[130:133], v[178:181], v[38:41]
	v_mfma_f32_16x16x32_bf16 v[30:33], v[138:141], v[178:181], v[30:33]
	v_mfma_f32_16x16x32_bf16 v[22:25], v[130:133], v[186:189], v[22:25]
	v_mfma_f32_16x16x32_bf16 v[14:17], v[138:141], v[186:189], v[14:17]
	v_mfma_f32_16x16x32_bf16 v[62:65], v[134:137], v[166:169], v[62:65]
	v_mfma_f32_16x16x32_bf16 v[58:61], v[142:145], v[166:169], v[58:61]
	v_mfma_f32_16x16x32_bf16 v[54:57], v[134:137], v[174:177], v[54:57]
	v_mfma_f32_16x16x32_bf16 v[46:49], v[142:145], v[174:177], v[46:49]
	v_mfma_f32_16x16x32_bf16 v[38:41], v[134:137], v[182:185], v[38:41]
	v_mfma_f32_16x16x32_bf16 v[30:33], v[142:145], v[182:185], v[30:33]
	v_mfma_f32_16x16x32_bf16 v[22:25], v[134:137], v[190:193], v[22:25]
	v_mfma_f32_16x16x32_bf16 v[14:17], v[142:145], v[190:193], v[14:17]
	s_setprio 0
	s_setprio 1
	v_mfma_f32_16x16x32_bf16 v[50:53], v[146:149], v[162:165], v[50:53]
	v_mfma_f32_16x16x32_bf16 v[42:45], v[154:157], v[162:165], v[42:45]
	v_mfma_f32_16x16x32_bf16 v[34:37], v[146:149], v[170:173], v[34:37]
	v_mfma_f32_16x16x32_bf16 v[26:29], v[154:157], v[170:173], v[26:29]
	v_mfma_f32_16x16x32_bf16 v[18:21], v[146:149], v[178:181], v[18:21]
	v_mfma_f32_16x16x32_bf16 v[10:13], v[154:157], v[178:181], v[10:13]
	v_mfma_f32_16x16x32_bf16 v[6:9], v[146:149], v[186:189], v[6:9]
	v_mfma_f32_16x16x32_bf16 v[2:5], v[154:157], v[186:189], v[2:5]
	v_mfma_f32_16x16x32_bf16 v[50:53], v[150:153], v[166:169], v[50:53]
	v_mfma_f32_16x16x32_bf16 v[42:45], v[158:161], v[166:169], v[42:45]
	v_mfma_f32_16x16x32_bf16 v[34:37], v[150:153], v[174:177], v[34:37]
	v_mfma_f32_16x16x32_bf16 v[26:29], v[158:161], v[174:177], v[26:29]
	v_mfma_f32_16x16x32_bf16 v[18:21], v[150:153], v[182:185], v[18:21]
	v_mfma_f32_16x16x32_bf16 v[10:13], v[158:161], v[182:185], v[10:13]
	v_mfma_f32_16x16x32_bf16 v[6:9], v[150:153], v[190:193], v[6:9]
	v_mfma_f32_16x16x32_bf16 v[2:5], v[158:161], v[190:193], v[2:5]
	s_setprio 0
	s_waitcnt vmcnt(8)
	s_barrier
	s_add_i32 s72, s72, 2
	s_add_u32 s26, s26, 0x100
	s_addc_u32 s27, s27, 0
	s_cmpk_gt_u32 s72, 0x55
	s_cbranch_scc1 .LBB0_1405

.LBB0_2224:
	s_waitcnt lgkmcnt(0)
	s_barrier
	s_setprio 1
	s_waitcnt lgkmcnt(0)
	v_mfma_f32_16x16x128_f8f6f4 v[126:129], v[26:33], v[58:65], v[126:129]
	v_mfma_f32_16x16x128_f8f6f4 v[122:125], v[18:25], v[58:65], v[122:125]
	v_mfma_f32_16x16x128_f8f6f4 v[110:113], v[26:33], v[50:57], v[110:113]
	v_mfma_f32_16x16x128_f8f6f4 v[106:109], v[18:25], v[50:57], v[106:109]
	v_mfma_f32_16x16x128_f8f6f4 v[94:97], v[26:33], v[42:49], v[94:97]
	v_mfma_f32_16x16x128_f8f6f4 v[90:93], v[18:25], v[42:49], v[90:93]
	v_mfma_f32_16x16x128_f8f6f4 v[78:81], v[26:33], v[34:41], v[78:81]
	v_mfma_f32_16x16x128_f8f6f4 v[74:77], v[18:25], v[34:41], v[74:77]
	s_setprio 0
	s_setprio 1
	v_mfma_f32_16x16x128_f8f6f4 v[118:121], v[10:17], v[58:65], v[118:121]
	v_mfma_f32_16x16x128_f8f6f4 v[114:117], v[2:9], v[58:65], v[114:117]
	v_mfma_f32_16x16x128_f8f6f4 v[102:105], v[10:17], v[50:57], v[102:105]
	v_mfma_f32_16x16x128_f8f6f4 v[98:101], v[2:9], v[50:57], v[98:101]
	v_mfma_f32_16x16x128_f8f6f4 v[86:89], v[10:17], v[42:49], v[86:89]
	v_mfma_f32_16x16x128_f8f6f4 v[82:85], v[2:9], v[42:49], v[82:85]
	v_mfma_f32_16x16x128_f8f6f4 v[70:73], v[10:17], v[34:41], v[70:73]
	v_mfma_f32_16x16x128_f8f6f4 v[66:69], v[2:9], v[34:41], v[66:69]
	s_setprio 0
	s_barrier
	v_add_u32_e32 v14, s48, v222
	v_add_u32_e32 v30, s53, v222
	ds_read_b128 v[2:5], v14
	ds_read_b128 v[6:9], v14 offset:1024
	ds_read_b128 v[10:13], v14 offset:2048
	ds_read_b128 v[14:17], v14 offset:3072
	ds_read_b128 v[18:21], v30
	ds_read_b128 v[22:25], v30 offset:1024
	ds_read_b128 v[26:29], v30 offset:2048
	ds_read_b128 v[30:33], v30 offset:3072
	s_add_u32 s28, s28, 0x530000
	s_addc_u32 s29, s29, 0
	s_mov_b32 m0, s42
	v_lshl_add_u64 v[228:229], s[28:29], 0, v[194:195]
	ds_read_b128 v[34:37], v226 offset:32768
	ds_read_b128 v[38:41], v226 offset:33792
	ds_read_b128 v[42:45], v226 offset:34816
	ds_read_b128 v[46:49], v226 offset:35840
	ds_read_b128 v[50:53], v226 offset:36864
	ds_read_b128 v[54:57], v226 offset:37888
	ds_read_b128 v[58:61], v226 offset:38912
	ds_read_b128 v[62:65], v226 offset:39936
	global_load_lds_dwordx4 v[228:229], off
	v_lshl_add_u64 v[228:229], s[28:29], 0, v[198:199]
	s_mov_b32 m0, s43
	s_nop 0
	global_load_lds_dwordx4 v[228:229], off
	s_waitcnt lgkmcnt(0)
	s_barrier
	s_setprio 1
	s_waitcnt lgkmcnt(0)
	v_mfma_f32_16x16x128_f8f6f4 v[190:193], v[2:9], v[34:41], v[190:193]
	v_mfma_f32_16x16x128_f8f6f4 v[186:189], v[10:17], v[34:41], v[186:189]
	v_mfma_f32_16x16x128_f8f6f4 v[174:177], v[2:9], v[42:49], v[174:177]
	v_mfma_f32_16x16x128_f8f6f4 v[170:173], v[10:17], v[42:49], v[170:173]
	v_mfma_f32_16x16x128_f8f6f4 v[158:161], v[2:9], v[50:57], v[158:161]
	v_mfma_f32_16x16x128_f8f6f4 v[154:157], v[10:17], v[50:57], v[154:157]
	v_mfma_f32_16x16x128_f8f6f4 v[142:145], v[2:9], v[58:65], v[142:145]
	v_mfma_f32_16x16x128_f8f6f4 v[138:141], v[10:17], v[58:65], v[138:141]
	s_setprio 0
	s_setprio 1
	v_mfma_f32_16x16x128_f8f6f4 v[182:185], v[18:25], v[34:41], v[182:185]
	v_mfma_f32_16x16x128_f8f6f4 v[178:181], v[26:33], v[34:41], v[178:181]
	v_mfma_f32_16x16x128_f8f6f4 v[166:169], v[18:25], v[42:49], v[166:169]
	v_mfma_f32_16x16x128_f8f6f4 v[162:165], v[26:33], v[42:49], v[162:165]
	v_mfma_f32_16x16x128_f8f6f4 v[150:153], v[18:25], v[50:57], v[150:153]
	v_mfma_f32_16x16x128_f8f6f4 v[146:149], v[26:33], v[50:57], v[146:149]
	v_mfma_f32_16x16x128_f8f6f4 v[134:137], v[18:25], v[58:65], v[134:137]
	v_mfma_f32_16x16x128_f8f6f4 v[130:133], v[26:33], v[58:65], v[130:133]
	s_setprio 0
	s_waitcnt vmcnt(8)
	s_barrier
	s_mov_b32 m0, s49
	v_lshl_add_u64 v[214:215], v[214:215], 0, s[14:15]
	s_add_u32 s26, s26, 0x40080
	ds_read_b128 v[34:37], v226 offset:49152
	ds_read_b128 v[38:41], v226 offset:50176
	ds_read_b128 v[42:45], v226 offset:51200
	ds_read_b128 v[46:49], v226 offset:52224
	ds_read_b128 v[50:53], v226 offset:53248
	ds_read_b128 v[54:57], v226 offset:54272
	ds_read_b128 v[58:61], v226 offset:55296
	ds_read_b128 v[62:65], v226 offset:56320
	global_load_lds_dwordx4 v[214:215], off
	v_lshl_add_u64 v[214:215], v[216:217], 0, s[14:15]
	s_mov_b32 m0, s50
	s_addc_u32 s27, s27, 0
	global_load_lds_dwordx4 v[214:215], off
	v_lshl_add_u64 v[214:215], s[26:27], 0, v[196:197]
	s_mov_b32 m0, s54
	s_nop 0
	global_load_lds_dwordx4 v[214:215], off
	v_lshl_add_u64 v[214:215], s[26:27], 0, v[200:201]
	s_mov_b32 m0, s55
	s_nop 0
	global_load_lds_dwordx4 v[214:215], off
	v_lshl_add_u64 v[214:215], v[218:219], 0, s[16:17]
	s_mov_b32 m0, s51
	s_nop 0
	global_load_lds_dwordx4 v[214:215], off
	v_lshl_add_u64 v[214:215], v[220:221], 0, s[16:17]
	s_mov_b32 m0, s52
	s_nop 0
	global_load_lds_dwordx4 v[214:215], off
	s_waitcnt lgkmcnt(0)
	s_barrier
	s_setprio 1
	s_waitcnt lgkmcnt(0)
	v_mfma_f32_16x16x128_f8f6f4 v[126:129], v[2:9], v[34:41], v[126:129]
	v_mfma_f32_16x16x128_f8f6f4 v[122:125], v[10:17], v[34:41], v[122:125]
	v_mfma_f32_16x16x128_f8f6f4 v[110:113], v[2:9], v[42:49], v[110:113]
	v_mfma_f32_16x16x128_f8f6f4 v[106:109], v[10:17], v[42:49], v[106:109]
	v_mfma_f32_16x16x128_f8f6f4 v[94:97], v[2:9], v[50:57], v[94:97]
	v_mfma_f32_16x16x128_f8f6f4 v[90:93], v[10:17], v[50:57], v[90:93]
	v_mfma_f32_16x16x128_f8f6f4 v[78:81], v[2:9], v[58:65], v[78:81]
	v_mfma_f32_16x16x128_f8f6f4 v[74:77], v[10:17], v[58:65], v[74:77]
	s_setprio 0
	s_setprio 1
	v_mfma_f32_16x16x128_f8f6f4 v[118:121], v[18:25], v[34:41], v[118:121]
	v_mfma_f32_16x16x128_f8f6f4 v[114:117], v[26:33], v[34:41], v[114:117]
	v_mfma_f32_16x16x128_f8f6f4 v[102:105], v[18:25], v[42:49], v[102:105]
	v_mfma_f32_16x16x128_f8f6f4 v[98:101], v[26:33], v[42:49], v[98:101]
	v_mfma_f32_16x16x128_f8f6f4 v[86:89], v[18:25], v[50:57], v[86:89]
	v_mfma_f32_16x16x128_f8f6f4 v[82:85], v[26:33], v[50:57], v[82:85]
	v_mfma_f32_16x16x128_f8f6f4 v[70:73], v[18:25], v[58:65], v[70:73]
	v_mfma_f32_16x16x128_f8f6f4 v[66:69], v[26:33], v[58:65], v[66:69]
	s_setprio 0
	s_waitcnt vmcnt(8)
	s_barrier
	s_add_i32 s69, s69, 2
	s_add_u32 s6, s6, 0x200
	s_addc_u32 s7, s7, 0
	s_add_u32 s67, s67, 0x100
	s_addc_u32 s68, s68, 0
	s_cmp_gt_u32 s69, 13
	s_cbranch_scc1 .LBB0_2232

.LBB0_2409:
	s_waitcnt lgkmcnt(0)
	s_barrier
	s_setprio 1
	s_waitcnt lgkmcnt(0)
	v_mfma_f32_16x16x128_f8f6f4 v[126:129], v[26:33], v[58:65], v[126:129]
	v_mfma_f32_16x16x128_f8f6f4 v[122:125], v[18:25], v[58:65], v[122:125]
	v_mfma_f32_16x16x128_f8f6f4 v[114:117], v[26:33], v[50:57], v[114:117]
	v_mfma_f32_16x16x128_f8f6f4 v[106:109], v[18:25], v[50:57], v[106:109]
	v_mfma_f32_16x16x128_f8f6f4 v[98:101], v[26:33], v[42:49], v[98:101]
	v_mfma_f32_16x16x128_f8f6f4 v[90:93], v[18:25], v[42:49], v[90:93]
	v_mfma_f32_16x16x128_f8f6f4 v[82:85], v[26:33], v[34:41], v[82:85]
	v_mfma_f32_16x16x128_f8f6f4 v[74:77], v[18:25], v[34:41], v[74:77]
	s_setprio 0
	s_setprio 1
	v_mfma_f32_16x16x128_f8f6f4 v[118:121], v[10:17], v[58:65], v[118:121]
	v_mfma_f32_16x16x128_f8f6f4 v[110:113], v[2:9], v[58:65], v[110:113]
	v_mfma_f32_16x16x128_f8f6f4 v[102:105], v[10:17], v[50:57], v[102:105]
	v_mfma_f32_16x16x128_f8f6f4 v[94:97], v[2:9], v[50:57], v[94:97]
	v_mfma_f32_16x16x128_f8f6f4 v[86:89], v[10:17], v[42:49], v[86:89]
	v_mfma_f32_16x16x128_f8f6f4 v[78:81], v[2:9], v[42:49], v[78:81]
	v_mfma_f32_16x16x128_f8f6f4 v[70:73], v[10:17], v[34:41], v[70:73]
	v_mfma_f32_16x16x128_f8f6f4 v[66:69], v[2:9], v[34:41], v[66:69]
	s_setprio 0
	s_barrier
	v_add_u32_e32 v14, s57, v222
	v_add_u32_e32 v30, s62, v222
	ds_read_b128 v[2:5], v14
	ds_read_b128 v[6:9], v14 offset:1024
	ds_read_b128 v[10:13], v14 offset:2048
	ds_read_b128 v[14:17], v14 offset:3072
	ds_read_b128 v[18:21], v30
	ds_read_b128 v[22:25], v30 offset:1024
	ds_read_b128 v[26:29], v30 offset:2048
	ds_read_b128 v[30:33], v30 offset:3072
	s_add_u32 s40, s40, 0x40000
	s_addc_u32 s41, s41, 0
	s_mov_b32 m0, s55
	v_lshl_add_u64 v[228:229], s[40:41], 0, v[194:195]
	ds_read_b128 v[34:37], v226 offset:32768
	ds_read_b128 v[38:41], v226 offset:33792
	ds_read_b128 v[42:45], v226 offset:34816
	ds_read_b128 v[46:49], v226 offset:35840
	ds_read_b128 v[50:53], v226 offset:36864
	ds_read_b128 v[54:57], v226 offset:37888
	ds_read_b128 v[58:61], v226 offset:38912
	ds_read_b128 v[62:65], v226 offset:39936
	global_load_lds_dwordx4 v[228:229], off
	v_lshl_add_u64 v[228:229], s[40:41], 0, v[198:199]
	s_mov_b32 m0, s56
	s_nop 0
	global_load_lds_dwordx4 v[228:229], off
	s_waitcnt lgkmcnt(0)
	s_barrier
	s_setprio 1
	s_waitcnt lgkmcnt(0)
	v_mfma_f32_16x16x128_f8f6f4 v[190:193], v[2:9], v[34:41], v[190:193]
	v_mfma_f32_16x16x128_f8f6f4 v[186:189], v[10:17], v[34:41], v[186:189]
	v_mfma_f32_16x16x128_f8f6f4 v[178:181], v[2:9], v[42:49], v[178:181]
	v_mfma_f32_16x16x128_f8f6f4 v[170:173], v[10:17], v[42:49], v[170:173]
	v_mfma_f32_16x16x128_f8f6f4 v[162:165], v[2:9], v[50:57], v[162:165]
	v_mfma_f32_16x16x128_f8f6f4 v[154:157], v[10:17], v[50:57], v[154:157]
	v_mfma_f32_16x16x128_f8f6f4 v[146:149], v[2:9], v[58:65], v[146:149]
	v_mfma_f32_16x16x128_f8f6f4 v[138:141], v[10:17], v[58:65], v[138:141]
	s_setprio 0
	s_setprio 1
	v_mfma_f32_16x16x128_f8f6f4 v[182:185], v[18:25], v[34:41], v[182:185]
	v_mfma_f32_16x16x128_f8f6f4 v[174:177], v[26:33], v[34:41], v[174:177]
	v_mfma_f32_16x16x128_f8f6f4 v[166:169], v[18:25], v[42:49], v[166:169]
	v_mfma_f32_16x16x128_f8f6f4 v[158:161], v[26:33], v[42:49], v[158:161]
	v_mfma_f32_16x16x128_f8f6f4 v[150:153], v[18:25], v[50:57], v[150:153]
	v_mfma_f32_16x16x128_f8f6f4 v[142:145], v[26:33], v[50:57], v[142:145]
	v_mfma_f32_16x16x128_f8f6f4 v[134:137], v[18:25], v[58:65], v[134:137]
	v_mfma_f32_16x16x128_f8f6f4 v[130:133], v[26:33], v[58:65], v[130:133]
	s_setprio 0
	s_waitcnt vmcnt(8)
	s_barrier
	s_mov_b32 m0, s58
	v_lshl_add_u64 v[214:215], v[214:215], 0, s[6:7]
	s_add_u32 s38, s38, 0x40080
	ds_read_b128 v[34:37], v226 offset:49152
	ds_read_b128 v[38:41], v226 offset:50176
	ds_read_b128 v[42:45], v226 offset:51200
	ds_read_b128 v[46:49], v226 offset:52224
	ds_read_b128 v[50:53], v226 offset:53248
	ds_read_b128 v[54:57], v226 offset:54272
	ds_read_b128 v[58:61], v226 offset:55296
	ds_read_b128 v[62:65], v226 offset:56320
	global_load_lds_dwordx4 v[214:215], off
	v_lshl_add_u64 v[214:215], v[216:217], 0, s[6:7]
	s_mov_b32 m0, s59
	s_addc_u32 s39, s39, 0
	global_load_lds_dwordx4 v[214:215], off
	v_lshl_add_u64 v[214:215], s[38:39], 0, v[196:197]
	s_mov_b32 m0, s63
	s_nop 0
	global_load_lds_dwordx4 v[214:215], off
	v_lshl_add_u64 v[214:215], s[38:39], 0, v[200:201]
	s_mov_b32 m0, s64
	s_nop 0
	global_load_lds_dwordx4 v[214:215], off
	v_lshl_add_u64 v[214:215], v[218:219], 0, s[6:7]
	s_mov_b32 m0, s60
	s_nop 0
	global_load_lds_dwordx4 v[214:215], off
	v_lshl_add_u64 v[214:215], v[220:221], 0, s[6:7]
	s_mov_b32 m0, s61
	s_nop 0
	global_load_lds_dwordx4 v[214:215], off
	s_waitcnt lgkmcnt(0)
	s_barrier
	s_setprio 1
	s_waitcnt lgkmcnt(0)
	v_mfma_f32_16x16x128_f8f6f4 v[126:129], v[2:9], v[34:41], v[126:129]
	v_mfma_f32_16x16x128_f8f6f4 v[122:125], v[10:17], v[34:41], v[122:125]
	v_mfma_f32_16x16x128_f8f6f4 v[114:117], v[2:9], v[42:49], v[114:117]
	v_mfma_f32_16x16x128_f8f6f4 v[106:109], v[10:17], v[42:49], v[106:109]
	v_mfma_f32_16x16x128_f8f6f4 v[98:101], v[2:9], v[50:57], v[98:101]
	v_mfma_f32_16x16x128_f8f6f4 v[90:93], v[10:17], v[50:57], v[90:93]
	v_mfma_f32_16x16x128_f8f6f4 v[82:85], v[2:9], v[58:65], v[82:85]
	v_mfma_f32_16x16x128_f8f6f4 v[74:77], v[10:17], v[58:65], v[74:77]
	s_setprio 0
	s_setprio 1
	v_mfma_f32_16x16x128_f8f6f4 v[118:121], v[18:25], v[34:41], v[118:121]
	v_mfma_f32_16x16x128_f8f6f4 v[110:113], v[26:33], v[34:41], v[110:113]
	v_mfma_f32_16x16x128_f8f6f4 v[102:105], v[18:25], v[42:49], v[102:105]
	v_mfma_f32_16x16x128_f8f6f4 v[94:97], v[26:33], v[42:49], v[94:97]
	v_mfma_f32_16x16x128_f8f6f4 v[86:89], v[18:25], v[50:57], v[86:89]
	v_mfma_f32_16x16x128_f8f6f4 v[78:81], v[26:33], v[50:57], v[78:81]
	v_mfma_f32_16x16x128_f8f6f4 v[70:73], v[18:25], v[58:65], v[70:73]
	v_mfma_f32_16x16x128_f8f6f4 v[66:69], v[26:33], v[58:65], v[66:69]
	s_setprio 0
	s_waitcnt vmcnt(8)
	s_barrier
	s_add_i32 s76, s76, 2
	s_add_u32 s36, s36, 0x100
	s_addc_u32 s37, s37, 0
	s_cmp_gt_u32 s76, 13
	s_cbranch_scc1 .LBB0_2417

.LBB0_2741:
	s_waitcnt lgkmcnt(0)
	s_barrier
	s_setprio 1
	s_waitcnt lgkmcnt(0)
	v_mfma_f32_16x16x32_bf16 v[62:65], v[146:149], v[186:189], v[62:65]
	v_mfma_f32_16x16x32_bf16 v[58:61], v[154:157], v[186:189], v[58:61]
	v_mfma_f32_16x16x32_bf16 v[54:57], v[146:149], v[178:181], v[54:57]
	v_mfma_f32_16x16x32_bf16 v[46:49], v[154:157], v[178:181], v[46:49]
	v_mfma_f32_16x16x32_bf16 v[38:41], v[146:149], v[170:173], v[38:41]
	v_mfma_f32_16x16x32_bf16 v[30:33], v[154:157], v[170:173], v[30:33]
	v_mfma_f32_16x16x32_bf16 v[22:25], v[146:149], v[162:165], v[22:25]
	v_mfma_f32_16x16x32_bf16 v[14:17], v[154:157], v[162:165], v[14:17]
	v_mfma_f32_16x16x32_bf16 v[62:65], v[150:153], v[190:193], v[62:65]
	v_mfma_f32_16x16x32_bf16 v[58:61], v[158:161], v[190:193], v[58:61]
	v_mfma_f32_16x16x32_bf16 v[54:57], v[150:153], v[182:185], v[54:57]
	v_mfma_f32_16x16x32_bf16 v[46:49], v[158:161], v[182:185], v[46:49]
	v_mfma_f32_16x16x32_bf16 v[38:41], v[150:153], v[174:177], v[38:41]
	v_mfma_f32_16x16x32_bf16 v[30:33], v[158:161], v[174:177], v[30:33]
	v_mfma_f32_16x16x32_bf16 v[22:25], v[150:153], v[166:169], v[22:25]
	v_mfma_f32_16x16x32_bf16 v[14:17], v[158:161], v[166:169], v[14:17]
	s_setprio 0
	s_setprio 1
	v_mfma_f32_16x16x32_bf16 v[50:53], v[130:133], v[186:189], v[50:53]
	v_mfma_f32_16x16x32_bf16 v[42:45], v[138:141], v[186:189], v[42:45]
	v_mfma_f32_16x16x32_bf16 v[34:37], v[130:133], v[178:181], v[34:37]
	v_mfma_f32_16x16x32_bf16 v[26:29], v[138:141], v[178:181], v[26:29]
	v_mfma_f32_16x16x32_bf16 v[18:21], v[130:133], v[170:173], v[18:21]
	v_mfma_f32_16x16x32_bf16 v[10:13], v[138:141], v[170:173], v[10:13]
	v_mfma_f32_16x16x32_bf16 v[6:9], v[130:133], v[162:165], v[6:9]
	v_mfma_f32_16x16x32_bf16 v[2:5], v[138:141], v[162:165], v[2:5]
	v_mfma_f32_16x16x32_bf16 v[50:53], v[134:137], v[190:193], v[50:53]
	v_mfma_f32_16x16x32_bf16 v[42:45], v[142:145], v[190:193], v[42:45]
	v_mfma_f32_16x16x32_bf16 v[34:37], v[134:137], v[182:185], v[34:37]
	v_mfma_f32_16x16x32_bf16 v[26:29], v[142:145], v[182:185], v[26:29]
	v_mfma_f32_16x16x32_bf16 v[18:21], v[134:137], v[174:177], v[18:21]
	v_mfma_f32_16x16x32_bf16 v[10:13], v[142:145], v[174:177], v[10:13]
	v_mfma_f32_16x16x32_bf16 v[6:9], v[134:137], v[166:169], v[6:9]
	v_mfma_f32_16x16x32_bf16 v[2:5], v[142:145], v[166:169], v[2:5]
	s_setprio 0
	s_barrier
	v_add_u32_e32 v142, s48, v222
	v_add_u32_e32 v158, s53, v222
	ds_read_b128 v[130:133], v142
	ds_read_b128 v[134:137], v142 offset:1024
	ds_read_b128 v[138:141], v142 offset:2048
	ds_read_b128 v[142:145], v142 offset:3072
	ds_read_b128 v[146:149], v158
	ds_read_b128 v[150:153], v158 offset:1024
	ds_read_b128 v[154:157], v158 offset:2048
	ds_read_b128 v[158:161], v158 offset:3072
	s_add_u32 s30, s30, 0x160000
	s_addc_u32 s31, s31, 0
	s_mov_b32 m0, s46
	v_lshl_add_u64 v[228:229], s[30:31], 0, v[194:195]
	ds_read_b128 v[162:165], v226 offset:32768
	ds_read_b128 v[166:169], v226 offset:33792
	ds_read_b128 v[170:173], v226 offset:34816
	ds_read_b128 v[174:177], v226 offset:35840
	ds_read_b128 v[178:181], v226 offset:36864
	ds_read_b128 v[182:185], v226 offset:37888
	ds_read_b128 v[186:189], v226 offset:38912
	ds_read_b128 v[190:193], v226 offset:39936
	global_load_lds_dwordx4 v[228:229], off
	v_lshl_add_u64 v[228:229], s[30:31], 0, v[198:199]
	s_mov_b32 m0, s47
	s_nop 0
	global_load_lds_dwordx4 v[228:229], off
	s_waitcnt lgkmcnt(0)
	s_barrier
	s_setprio 1
	s_waitcnt lgkmcnt(0)
	v_mfma_f32_16x16x32_bf16 v[126:129], v[130:133], v[162:165], v[126:129]
	v_mfma_f32_16x16x32_bf16 v[122:125], v[138:141], v[162:165], v[122:125]
	v_mfma_f32_16x16x32_bf16 v[118:121], v[130:133], v[170:173], v[118:121]
	v_mfma_f32_16x16x32_bf16 v[110:113], v[138:141], v[170:173], v[110:113]
	v_mfma_f32_16x16x32_bf16 v[102:105], v[130:133], v[178:181], v[102:105]
	v_mfma_f32_16x16x32_bf16 v[94:97], v[138:141], v[178:181], v[94:97]
	v_mfma_f32_16x16x32_bf16 v[86:89], v[130:133], v[186:189], v[86:89]
	v_mfma_f32_16x16x32_bf16 v[78:81], v[138:141], v[186:189], v[78:81]
	v_mfma_f32_16x16x32_bf16 v[126:129], v[134:137], v[166:169], v[126:129]
	v_mfma_f32_16x16x32_bf16 v[122:125], v[142:145], v[166:169], v[122:125]
	v_mfma_f32_16x16x32_bf16 v[118:121], v[134:137], v[174:177], v[118:121]
	v_mfma_f32_16x16x32_bf16 v[110:113], v[142:145], v[174:177], v[110:113]
	v_mfma_f32_16x16x32_bf16 v[102:105], v[134:137], v[182:185], v[102:105]
	v_mfma_f32_16x16x32_bf16 v[94:97], v[142:145], v[182:185], v[94:97]
	v_mfma_f32_16x16x32_bf16 v[86:89], v[134:137], v[190:193], v[86:89]
	v_mfma_f32_16x16x32_bf16 v[78:81], v[142:145], v[190:193], v[78:81]
	s_setprio 0
	s_setprio 1
	v_mfma_f32_16x16x32_bf16 v[114:117], v[146:149], v[162:165], v[114:117]
	v_mfma_f32_16x16x32_bf16 v[106:109], v[154:157], v[162:165], v[106:109]
	v_mfma_f32_16x16x32_bf16 v[98:101], v[146:149], v[170:173], v[98:101]
	v_mfma_f32_16x16x32_bf16 v[90:93], v[154:157], v[170:173], v[90:93]
	v_mfma_f32_16x16x32_bf16 v[82:85], v[146:149], v[178:181], v[82:85]
	v_mfma_f32_16x16x32_bf16 v[74:77], v[154:157], v[178:181], v[74:77]
	v_mfma_f32_16x16x32_bf16 v[70:73], v[146:149], v[186:189], v[70:73]
	v_mfma_f32_16x16x32_bf16 v[66:69], v[154:157], v[186:189], v[66:69]
	v_mfma_f32_16x16x32_bf16 v[114:117], v[150:153], v[166:169], v[114:117]
	v_mfma_f32_16x16x32_bf16 v[106:109], v[158:161], v[166:169], v[106:109]
	v_mfma_f32_16x16x32_bf16 v[98:101], v[150:153], v[174:177], v[98:101]
	v_mfma_f32_16x16x32_bf16 v[90:93], v[158:161], v[174:177], v[90:93]
	v_mfma_f32_16x16x32_bf16 v[82:85], v[150:153], v[182:185], v[82:85]
	v_mfma_f32_16x16x32_bf16 v[74:77], v[158:161], v[182:185], v[74:77]
	v_mfma_f32_16x16x32_bf16 v[70:73], v[150:153], v[190:193], v[70:73]
	v_mfma_f32_16x16x32_bf16 v[66:69], v[158:161], v[190:193], v[66:69]
	s_setprio 0
	s_waitcnt vmcnt(8)
	s_barrier
	s_mov_b32 m0, s49
	v_lshl_add_u64 v[214:215], v[214:215], 0, s[8:9]
	s_add_u32 s28, s28, 0x160080
	ds_read_b128 v[162:165], v226 offset:49152
	ds_read_b128 v[166:169], v226 offset:50176
	ds_read_b128 v[170:173], v226 offset:51200
	ds_read_b128 v[174:177], v226 offset:52224
	ds_read_b128 v[178:181], v226 offset:53248
	ds_read_b128 v[182:185], v226 offset:54272
	ds_read_b128 v[186:189], v226 offset:55296
	ds_read_b128 v[190:193], v226 offset:56320
	global_load_lds_dwordx4 v[214:215], off
	v_lshl_add_u64 v[214:215], v[216:217], 0, s[8:9]
	s_mov_b32 m0, s50
	s_addc_u32 s29, s29, 0
	global_load_lds_dwordx4 v[214:215], off
	v_lshl_add_u64 v[214:215], s[28:29], 0, v[196:197]
	s_mov_b32 m0, s54
	s_nop 0
	global_load_lds_dwordx4 v[214:215], off
	v_lshl_add_u64 v[214:215], s[28:29], 0, v[200:201]
	s_mov_b32 m0, s55
	s_nop 0
	global_load_lds_dwordx4 v[214:215], off
	v_lshl_add_u64 v[214:215], v[218:219], 0, s[8:9]
	s_mov_b32 m0, s51
	s_nop 0
	global_load_lds_dwordx4 v[214:215], off
	v_lshl_add_u64 v[214:215], v[220:221], 0, s[8:9]
	s_mov_b32 m0, s52
	s_nop 0
	global_load_lds_dwordx4 v[214:215], off
	s_waitcnt lgkmcnt(0)
	s_barrier
	s_setprio 1
	s_waitcnt lgkmcnt(0)
	v_mfma_f32_16x16x32_bf16 v[62:65], v[130:133], v[162:165], v[62:65]
	v_mfma_f32_16x16x32_bf16 v[58:61], v[138:141], v[162:165], v[58:61]
	v_mfma_f32_16x16x32_bf16 v[54:57], v[130:133], v[170:173], v[54:57]
	v_mfma_f32_16x16x32_bf16 v[46:49], v[138:141], v[170:173], v[46:49]
	v_mfma_f32_16x16x32_bf16 v[38:41], v[130:133], v[178:181], v[38:41]
	v_mfma_f32_16x16x32_bf16 v[30:33], v[138:141], v[178:181], v[30:33]
	v_mfma_f32_16x16x32_bf16 v[22:25], v[130:133], v[186:189], v[22:25]
	v_mfma_f32_16x16x32_bf16 v[14:17], v[138:141], v[186:189], v[14:17]
	v_mfma_f32_16x16x32_bf16 v[62:65], v[134:137], v[166:169], v[62:65]
	v_mfma_f32_16x16x32_bf16 v[58:61], v[142:145], v[166:169], v[58:61]
	v_mfma_f32_16x16x32_bf16 v[54:57], v[134:137], v[174:177], v[54:57]
	v_mfma_f32_16x16x32_bf16 v[46:49], v[142:145], v[174:177], v[46:49]
	v_mfma_f32_16x16x32_bf16 v[38:41], v[134:137], v[182:185], v[38:41]
	v_mfma_f32_16x16x32_bf16 v[30:33], v[142:145], v[182:185], v[30:33]
	v_mfma_f32_16x16x32_bf16 v[22:25], v[134:137], v[190:193], v[22:25]
	v_mfma_f32_16x16x32_bf16 v[14:17], v[142:145], v[190:193], v[14:17]
	s_setprio 0
	s_setprio 1
	v_mfma_f32_16x16x32_bf16 v[50:53], v[146:149], v[162:165], v[50:53]
	v_mfma_f32_16x16x32_bf16 v[42:45], v[154:157], v[162:165], v[42:45]
	v_mfma_f32_16x16x32_bf16 v[34:37], v[146:149], v[170:173], v[34:37]
	v_mfma_f32_16x16x32_bf16 v[26:29], v[154:157], v[170:173], v[26:29]
	v_mfma_f32_16x16x32_bf16 v[18:21], v[146:149], v[178:181], v[18:21]
	v_mfma_f32_16x16x32_bf16 v[10:13], v[154:157], v[178:181], v[10:13]
	v_mfma_f32_16x16x32_bf16 v[6:9], v[146:149], v[186:189], v[6:9]
	v_mfma_f32_16x16x32_bf16 v[2:5], v[154:157], v[186:189], v[2:5]
	v_mfma_f32_16x16x32_bf16 v[50:53], v[150:153], v[166:169], v[50:53]
	v_mfma_f32_16x16x32_bf16 v[42:45], v[158:161], v[166:169], v[42:45]
	v_mfma_f32_16x16x32_bf16 v[34:37], v[150:153], v[174:177], v[34:37]
	v_mfma_f32_16x16x32_bf16 v[26:29], v[158:161], v[174:177], v[26:29]
	v_mfma_f32_16x16x32_bf16 v[18:21], v[150:153], v[182:185], v[18:21]
	v_mfma_f32_16x16x32_bf16 v[10:13], v[158:161], v[182:185], v[10:13]
	v_mfma_f32_16x16x32_bf16 v[6:9], v[150:153], v[190:193], v[6:9]
	v_mfma_f32_16x16x32_bf16 v[2:5], v[158:161], v[190:193], v[2:5]
	s_setprio 0
	s_waitcnt vmcnt(8)
	s_barrier
	s_add_i32 s69, s69, 2
	s_add_u32 s26, s26, 0x100
	s_addc_u32 s27, s27, 0
	s_cmpk_gt_u32 s69, 0x55
	s_cbranch_scc1 .LBB0_2749
